# diff attention: LDS fragment prefetch 8 MFMAs ahead, Q in regs, setprio, stores at segment head
# speedup vs baseline: 1.0397x; 1.0222x over previous
.LBB0_1049:
	s_waitcnt lgkmcnt(0)
	s_barrier
	s_setprio 1
	v_add3_u32 v0, s57, v152, v153
	s_waitcnt vmcnt(4)
	ds_write_b128 v0, v[86:89]
	v_add3_u32 v0, s57, v154, v155
	s_waitcnt vmcnt(3)
	ds_write_b128 v0, v[90:93]
	v_add3_u32 v0, s57, v156, v140
	ds_write_b128 v0, v[82:85] offset:13312
	s_and_b64 vcc, exec, s[4:5]
	s_cbranch_vccnz .LBB0_1051
	v_add_u32_e32 v249, s60, v157
	ds_read_b128 v[236:239], v249
	ds_read_b128 v[240:243], v249 offset:6656
	ds_read_b128 v[244:247], v249 offset:32
	v_mfma_f32_32x32x16_bf16 v[2:17], v[164:167], v[122:125], v[2:17]
	ds_read_b128 v[164:167], v249 offset:6688
	v_mfma_f32_32x32x16_bf16 v[18:33], v[168:171], v[122:125], v[18:33]
	ds_read_b128 v[168:171], v249 offset:64
	v_mfma_f32_32x32x16_bf16 v[2:17], v[172:175], v[126:129], v[2:17]
	ds_read_b128 v[172:175], v249 offset:6720
	v_mfma_f32_32x32x16_bf16 v[18:33], v[176:179], v[126:129], v[18:33]
	ds_read_b128 v[176:179], v249 offset:96
	v_mfma_f32_32x32x16_bf16 v[2:17], v[180:183], v[130:133], v[2:17]
	ds_read_b128 v[180:183], v249 offset:6752
	v_mfma_f32_32x32x16_bf16 v[18:33], v[220:223], v[130:133], v[18:33]
	ds_read_b128 v[220:223], v249 offset:128
	v_mfma_f32_32x32x16_bf16 v[2:17], v[224:227], v[134:137], v[2:17]
	ds_read_b128 v[224:227], v249 offset:6784
	v_mfma_f32_32x32x16_bf16 v[18:33], v[232:235], v[134:137], v[18:33]
	ds_read_b128 v[232:235], v249 offset:160

.LBB0_1053:
	s_setprio 0
	s_add_i32 s0, s59, 4
	s_cmp_lt_u32 s59, s48
	s_cselect_b32 s0, s0, s50
	s_lshl_b32 s8, s0, 6
	v_add_u32_e32 v0, s8, v150
	s_waitcnt lgkmcnt(0)
	s_barrier
	v_mad_i64_i32 v[82:83], s[0:1], v0, s3, v[144:145]
	v_add_u32_e32 v0, s8, v151
	v_mad_i64_i32 v[84:85], s[0:1], v0, s3, v[146:147]
	global_load_dwordx4 v[86:89], v[82:83], off
	global_load_dwordx4 v[90:93], v[84:85], off
	v_lshl_add_u64 v[82:83], s[8:9], 1, v[142:143]
	global_load_dwordx4 v[82:85], v[82:83], off
	v_add_u32_e32 v248, s60, v160
	ds_read_b128 v[164:167], v248 offset:13312
	ds_read_b128 v[168:171], v248 offset:17920
	ds_read_b128 v[172:175], v248 offset:13344
	ds_read_b128 v[176:179], v248 offset:17952
	ds_read_b128 v[180:183], v248 offset:13376
	ds_read_b128 v[220:223], v248 offset:17984
	ds_read_b128 v[224:227], v248 offset:13408
	ds_read_b128 v[232:235], v248 offset:18016
	s_add_i32 s62, s62, 1
	s_cmp_lt_i32 s62, 0
	s_cselect_b64 s[0:1], -1, 0
	s_add_i32 s4, s61, 64
	s_cmp_le_i32 s4, s51
	s_cselect_b64 s[4:5], -1, 0
	s_or_b64 s[0:1], s[0:1], s[4:5]
	v_cndmask_b32_e64 v0, 0, 1, s[0:1]
	v_cmp_ne_u32_e64 s[4:5], 1, v0
	s_andn2_b64 vcc, exec, s[0:1]
	s_cbranch_vccnz .LBB0_1059
	s_cmp_lt_i32 s62, 0
	s_cbranch_scc1 .LBB0_1056
	v_add_u32_e32 v0, s54, v161
	v_add_u32_e32 v107, 0x60, v0
	v_add_u32_e32 v106, 64, v0
	v_cmp_le_i32_e32 vcc, v107, v159
	s_nop 1
	v_cndmask_b32_e32 v50, v149, v50, vcc
	v_cmp_lt_i32_e32 vcc, v106, v159
	s_nop 1
	v_cndmask_b32_e32 v35, v149, v35, vcc
	v_cmp_le_i32_e32 vcc, v106, v159
	v_add_u32_e32 v106, 0x61, v0
	s_nop 0
	v_cndmask_b32_e32 v34, v149, v34, vcc
	v_cmp_le_i32_e32 vcc, v106, v159
	v_add_u32_e32 v106, 0x42, v0
	s_nop 0
	v_cndmask_b32_e32 v51, v149, v51, vcc
	v_cmp_le_i32_e32 vcc, v106, v159
	v_add_u32_e32 v106, 0x62, v0
	s_nop 0
	v_cndmask_b32_e32 v36, v149, v36, vcc
	v_cmp_le_i32_e32 vcc, v106, v159
	v_add_u32_e32 v106, 0x43, v0
	s_nop 0
	v_cndmask_b32_e32 v52, v149, v52, vcc
	v_cmp_le_i32_e32 vcc, v106, v159
	v_add_u32_e32 v106, 0x63, v0
	s_nop 0
	v_cndmask_b32_e32 v37, v149, v37, vcc
	v_cmp_le_i32_e32 vcc, v106, v159
	v_add_u32_e32 v106, 0x48, v0
	s_nop 0
	v_cndmask_b32_e32 v53, v149, v53, vcc
	v_cmp_le_i32_e32 vcc, v106, v159
	v_add_u32_e32 v106, 0x68, v0
	s_nop 0
	v_cndmask_b32_e32 v38, v149, v38, vcc
	v_cmp_le_i32_e32 vcc, v106, v159
	v_add_u32_e32 v106, 0x49, v0
	s_nop 0
	v_cndmask_b32_e32 v54, v149, v54, vcc
	v_cmp_le_i32_e32 vcc, v106, v159
	v_add_u32_e32 v106, 0x69, v0
	s_nop 0
	v_cndmask_b32_e32 v39, v149, v39, vcc
	v_cmp_le_i32_e32 vcc, v106, v159
	v_add_u32_e32 v106, 0x4a, v0
	s_nop 0
	v_cndmask_b32_e32 v55, v149, v55, vcc
	v_cmp_le_i32_e32 vcc, v106, v159
	v_add_u32_e32 v106, 0x6a, v0
	s_nop 0
	v_cndmask_b32_e32 v40, v149, v40, vcc
	v_cmp_le_i32_e32 vcc, v106, v159
	v_add_u32_e32 v106, 0x4b, v0
	s_nop 0
	v_cndmask_b32_e32 v56, v149, v56, vcc
	v_cmp_le_i32_e32 vcc, v106, v159
	v_add_u32_e32 v106, 0x6b, v0
	s_nop 0
	v_cndmask_b32_e32 v41, v149, v41, vcc
	v_cmp_le_i32_e32 vcc, v106, v159
	v_add_u32_e32 v106, 0x50, v0
	s_nop 0
	v_cndmask_b32_e32 v57, v149, v57, vcc
	v_cmp_le_i32_e32 vcc, v106, v159
	v_add_u32_e32 v106, 0x70, v0
	s_nop 0
	v_cndmask_b32_e32 v42, v149, v42, vcc
	v_cmp_le_i32_e32 vcc, v106, v159
	v_add_u32_e32 v106, 0x51, v0
	s_nop 0
	v_cndmask_b32_e32 v58, v149, v58, vcc
	v_cmp_le_i32_e32 vcc, v106, v159
	v_add_u32_e32 v106, 0x71, v0
	s_nop 0
	v_cndmask_b32_e32 v43, v149, v43, vcc
	v_cmp_le_i32_e32 vcc, v106, v159
	v_add_u32_e32 v106, 0x52, v0
	s_nop 0
	v_cndmask_b32_e32 v59, v149, v59, vcc
	v_cmp_le_i32_e32 vcc, v106, v159
	v_add_u32_e32 v106, 0x72, v0
	s_nop 0
	v_cndmask_b32_e32 v44, v149, v44, vcc
	v_cmp_le_i32_e32 vcc, v106, v159
	v_add_u32_e32 v106, 0x53, v0
	s_nop 0
	v_cndmask_b32_e32 v60, v149, v60, vcc
	v_cmp_le_i32_e32 vcc, v106, v159
	v_add_u32_e32 v106, 0x73, v0
	s_nop 0
	v_cndmask_b32_e32 v45, v149, v45, vcc
	v_cmp_le_i32_e32 vcc, v106, v159
	v_add_u32_e32 v106, 0x58, v0
	s_nop 0
	v_cndmask_b32_e32 v61, v149, v61, vcc
	v_cmp_le_i32_e32 vcc, v106, v159
	v_add_u32_e32 v106, 0x78, v0
	s_nop 0
	v_cndmask_b32_e32 v46, v149, v46, vcc
	v_cmp_le_i32_e32 vcc, v106, v159
	v_add_u32_e32 v106, 0x59, v0
	s_nop 0
	v_cndmask_b32_e32 v62, v149, v62, vcc
	v_cmp_le_i32_e32 vcc, v106, v159
	v_add_u32_e32 v106, 0x79, v0
	s_nop 0
	v_cndmask_b32_e32 v47, v149, v47, vcc
	v_cmp_le_i32_e32 vcc, v106, v159
	v_add_u32_e32 v106, 0x5a, v0
	s_nop 0
	v_cndmask_b32_e32 v63, v149, v63, vcc
	v_cmp_le_i32_e32 vcc, v106, v159
	v_add_u32_e32 v106, 0x7a, v0
	s_nop 0
	v_cndmask_b32_e32 v48, v149, v48, vcc
	v_cmp_le_i32_e32 vcc, v106, v159
	v_add_u32_e32 v106, 0x5b, v0
	v_add_u32_e32 v0, 0x7b, v0
	v_cndmask_b32_e32 v64, v149, v64, vcc
	v_cmp_le_i32_e32 vcc, v106, v159
	s_nop 1
	v_cndmask_b32_e32 v49, v149, v49, vcc
	v_cmp_le_i32_e32 vcc, v0, v159
	s_nop 1
	v_cndmask_b32_e32 v65, v149, v65, vcc

.LBB0_1059:
	s_waitcnt lgkmcnt(0)
	s_barrier
	s_setprio 1
	v_add3_u32 v0, s58, v152, v153
	s_waitcnt vmcnt(5)
	ds_write_b128 v0, v[98:101]
	v_add3_u32 v0, s58, v154, v155
	s_waitcnt vmcnt(4)
	ds_write_b128 v0, v[94:97]
	v_add3_u32 v0, s58, v156, v140
	s_waitcnt vmcnt(3)
	ds_write_b128 v0, v[102:105] offset:13312
	s_and_b64 vcc, exec, s[4:5]
	s_cbranch_vccnz .LBB0_1061
	v_add_u32_e32 v249, s57, v157
	ds_read_b128 v[236:239], v249
	ds_read_b128 v[240:243], v249 offset:6656
	ds_read_b128 v[244:247], v249 offset:32
	v_mfma_f32_32x32x16_bf16 v[2:17], v[164:167], v[106:109], v[2:17]
	ds_read_b128 v[164:167], v249 offset:6688
	v_mfma_f32_32x32x16_bf16 v[18:33], v[168:171], v[106:109], v[18:33]
	ds_read_b128 v[168:171], v249 offset:64
	v_mfma_f32_32x32x16_bf16 v[2:17], v[172:175], v[110:113], v[2:17]
	ds_read_b128 v[172:175], v249 offset:6720
	v_mfma_f32_32x32x16_bf16 v[18:33], v[176:179], v[110:113], v[18:33]
	ds_read_b128 v[176:179], v249 offset:96
	v_mfma_f32_32x32x16_bf16 v[2:17], v[180:183], v[114:117], v[2:17]
	ds_read_b128 v[180:183], v249 offset:6752
	v_mfma_f32_32x32x16_bf16 v[18:33], v[220:223], v[114:117], v[18:33]
	ds_read_b128 v[220:223], v249 offset:128
	v_mfma_f32_32x32x16_bf16 v[2:17], v[224:227], v[118:121], v[2:17]
	ds_read_b128 v[224:227], v249 offset:6784
	v_mfma_f32_32x32x16_bf16 v[18:33], v[232:235], v[118:121], v[18:33]
	ds_read_b128 v[232:235], v249 offset:160

; template <int DK, int DV>
; __device__ __forceinline__ void attn_unit(LAS unsigned char* lds, const bf16* Qp, int ldq, const bf16* Kp, int ldk, const bf16* VTp, bf16* Op, int ldo, int qb) {
;     ...
;     for (int t = 0; t < NT; t += 2) {
;         ATT_STEP(t, kra, vra, krb, vrb);
;         ATT_STEP(t + 1, krb, vrb, kra, vra);
;     }
.LBB0_1063:
	s_setprio 0
	s_waitcnt lgkmcnt(0)
	s_barrier
	s_addk_i32 s54, 0x80
	s_and_b64 vcc, exec, s[4:5]
	s_cbranch_vccnz .LBB0_1065
	s_mov_b32 s0, s57
	s_mov_b32 s57, s60
	s_branch .LBB0_1037

; #define ATT_BAR() do { asm volatile("s_waitcnt lgkmcnt(0)" ::: "memory"); __builtin_amdgcn_s_barrier(); asm volatile("" ::: "memory"); } while (0)
; template <int DK, int DV>
; __device__ __forceinline__ void attn_unit(LAS unsigned char* lds, const bf16* Qp, int ldq, const bf16* Kp, int ldk, const bf16* VTp, bf16* Op, int ldo, int qb) {
;     ...
;     float mrun = 0.f, lrun = 0.f;
;     f32x16 o[NDB];
; #pragma unroll
;     for (int db = 0; db < NDB; ++db)
; #pragma unroll
;         for (int r = 0; r < 16; ++r) o[db][r] = 0.f;
;     f32x16 s0, s1;
;     const f32x16 zacc = {0.f, 0.f, 0.f, 0.f, 0.f, 0.f, 0.f, 0.f, 0.f, 0.f, 0.f, 0.f, 0.f, 0.f, 0.f, 0.f};
;     f32x16 negm = zacc;
;     constexpr float ATT_THR = 8.f;
;     ATT_QK(0, zacc);
;     if (grpB) ATT_BAR();
;     int bcur = 0, bnext = BUF, bfree = 2 * BUF;
.LBB0_1071:
	ds_read_b128 v[232:235], v189
	ds_read_b128 v[236:239], v189 offset:1024
	ds_read_b128 v[240:243], v189 offset:2048
	ds_read_b128 v[244:247], v189 offset:3072
	v_mov_b32_e32 v14, v1
	v_mov_b32_e32 v15, v1
	s_lshl_b32 s43, s1, 2
	v_lshl_add_u64 v[182:183], v[2:3], 1, s[4:5]
	v_or_b32_e32 v192, s35, v4
	v_lshlrev_b32_e32 v191, 2, v5
	v_mov_b32_e32 v0, v1
	v_mov_b32_e32 v2, v1
	v_mov_b32_e32 v3, v1
	v_mov_b32_e32 v4, v1
	v_mov_b32_e32 v5, v1
	v_mov_b32_e32 v6, v1
	v_mov_b32_e32 v7, v1
	v_mov_b32_e32 v8, v1
	v_mov_b32_e32 v9, v1
	v_mov_b32_e32 v10, v1
	v_mov_b32_e32 v11, v1
	v_mov_b32_e32 v12, v1
	v_mov_b32_e32 v13, v1
	v_mov_b64_e32 v[30:31], v[14:15]
	v_mov_b64_e32 v[46:47], v[14:15]
	v_mov_b64_e32 v[62:63], v[14:15]
	v_mov_b64_e32 v[78:79], v[14:15]
	v_mov_b64_e32 v[126:127], v[14:15]
	s_lshl_b32 s42, s0, 13
	s_add_i32 s44, s43, 4
	s_or_b32 s45, s43, 3
	s_or_b32 s46, s35, 31
	s_mov_b32 s47, 0
	s_sub_i32 s48, 0, s43
	s_sub_i32 s49, 0, s8
	v_subrev_u32_e32 v194, s8, v191
	s_mov_b32 s50, 0xd800
	s_movk_i32 s51, 0x6c00
	v_mov_b32_e32 v193, 0
	v_mov_b64_e32 v[28:29], v[12:13]
	v_mov_b64_e32 v[26:27], v[10:11]
	v_mov_b64_e32 v[24:25], v[8:9]
	v_mov_b64_e32 v[22:23], v[6:7]
	v_mov_b64_e32 v[20:21], v[4:5]
	v_mov_b64_e32 v[18:19], v[2:3]
	v_mov_b64_e32 v[16:17], v[0:1]
	v_mov_b64_e32 v[44:45], v[12:13]
	v_mov_b64_e32 v[42:43], v[10:11]
	v_mov_b64_e32 v[40:41], v[8:9]
	v_mov_b64_e32 v[38:39], v[6:7]
	v_mov_b64_e32 v[36:37], v[4:5]
	v_mov_b64_e32 v[34:35], v[2:3]
	v_mov_b64_e32 v[32:33], v[0:1]
	v_mov_b64_e32 v[60:61], v[12:13]
	v_mov_b64_e32 v[58:59], v[10:11]
	v_mov_b64_e32 v[56:57], v[8:9]
	v_mov_b64_e32 v[54:55], v[6:7]
	v_mov_b64_e32 v[52:53], v[4:5]
	v_mov_b64_e32 v[50:51], v[2:3]
	v_mov_b64_e32 v[48:49], v[0:1]
	v_mov_b64_e32 v[76:77], v[12:13]
	v_mov_b64_e32 v[74:75], v[10:11]
	v_mov_b64_e32 v[72:73], v[8:9]
	v_mov_b64_e32 v[70:71], v[6:7]
	v_mov_b64_e32 v[68:69], v[4:5]
	v_mov_b64_e32 v[66:67], v[2:3]
	v_mov_b64_e32 v[64:65], v[0:1]
	v_mov_b32_e32 v195, 0
	v_mov_b64_e32 v[124:125], v[12:13]
	v_mov_b64_e32 v[122:123], v[10:11]
	v_mov_b64_e32 v[120:121], v[8:9]
	v_mov_b64_e32 v[118:119], v[6:7]
	v_mov_b64_e32 v[116:117], v[4:5]
	v_mov_b64_e32 v[114:115], v[2:3]
	v_mov_b64_e32 v[112:113], v[0:1]
	s_mov_b32 s0, 0
	s_mov_b32 s54, 0
.LBB0_1072:
	s_add_i32 s1, s54, 3
	s_cmp_lt_u32 s1, s44
	s_cselect_b32 s1, s1, s45
	s_lshl_b32 s8, s1, 6
	v_add_u32_e32 v2, s8, v174
	v_ashrrev_i32_e32 v3, 31, v2
	v_lshlrev_b64 v[2:3], 10, v[2:3]
	v_lshl_add_u64 v[6:7], s[8:9], 1, v[176:177]
	v_lshl_add_u64 v[2:3], v[182:183], 0, v[2:3]
	v_lshl_add_u64 v[4:5], v[6:7], 0, v[178:179]
	v_lshl_add_u64 v[6:7], v[6:7], 0, v[180:181]
	global_load_dwordx4 v[10:13], v[2:3], off
	s_nop 0
	global_load_dwordx4 v[2:5], v[4:5], off
	s_add_i32 s57, s48, s54
	global_load_dwordx4 v[6:9], v[6:7], off
	s_cmp_lt_i32 s57, 0
	s_cselect_b64 s[16:17], -1, 0
	s_add_i32 s56, s49, s47
	s_cmp_le_i32 s56, s46
	s_cselect_b64 s[4:5], -1, 0
	s_or_b64 s[18:19], s[16:17], s[4:5]
	v_cndmask_b32_e64 v0, 0, 1, s[18:19]
	s_mov_b32 s55, s51
	v_cmp_ne_u32_e64 s[4:5], 1, v0
	s_andn2_b64 vcc, exec, s[18:19]
	s_mov_b32 s51, s0
	v_add_u32_e32 v248, s51, v190
	ds_read_b128 v[196:199], v248 offset:9216
	ds_read_b128 v[200:203], v248 offset:13824
	ds_read_b128 v[204:207], v248 offset:18432
	ds_read_b128 v[208:211], v248 offset:23040
	ds_read_b128 v[212:215], v248 offset:9248
	ds_read_b128 v[216:219], v248 offset:13856
	ds_read_b128 v[220:223], v248 offset:18464
	ds_read_b128 v[224:227], v248 offset:23072
	s_cbranch_vccnz .LBB0_1084
	s_cmp_lt_i32 s57, 0
	s_cbranch_scc1 .LBB0_1075
	v_add_u32_e32 v0, s47, v194
	v_add_u32_e32 v14, 32, v0
	v_cmp_le_i32_e32 vcc, v14, v192
	v_add_u32_e32 v14, 33, v0
	s_nop 0
	v_cndmask_b32_e32 v96, v185, v96, vcc
	v_cmp_lt_i32_e32 vcc, v0, v192
	s_nop 1
	v_cndmask_b32_e32 v81, v185, v81, vcc
	v_cmp_le_i32_e32 vcc, v0, v192
	s_nop 1
	v_cndmask_b32_e32 v80, v185, v80, vcc
	v_cmp_le_i32_e32 vcc, v14, v192
	v_add_u32_e32 v14, 2, v0
	s_nop 0
	v_cndmask_b32_e32 v97, v185, v97, vcc
	v_cmp_le_i32_e32 vcc, v14, v192
	v_add_u32_e32 v14, 34, v0
	s_nop 0
	v_cndmask_b32_e32 v82, v185, v82, vcc
	v_cmp_le_i32_e32 vcc, v14, v192
	v_add_u32_e32 v14, 3, v0
	s_nop 0
	v_cndmask_b32_e32 v98, v185, v98, vcc
	v_cmp_le_i32_e32 vcc, v14, v192
	v_add_u32_e32 v14, 35, v0
	s_nop 0
	v_cndmask_b32_e32 v83, v185, v83, vcc
	v_cmp_le_i32_e32 vcc, v14, v192
	v_add_u32_e32 v14, 8, v0
	s_nop 0
	v_cndmask_b32_e32 v99, v185, v99, vcc
	v_cmp_le_i32_e32 vcc, v14, v192
	v_add_u32_e32 v14, 40, v0
	s_nop 0
	v_cndmask_b32_e32 v84, v185, v84, vcc
	v_cmp_le_i32_e32 vcc, v14, v192
	v_add_u32_e32 v14, 9, v0
	s_nop 0
	v_cndmask_b32_e32 v100, v185, v100, vcc
	v_cmp_le_i32_e32 vcc, v14, v192
	v_add_u32_e32 v14, 41, v0
	s_nop 0
	v_cndmask_b32_e32 v85, v185, v85, vcc
	v_cmp_le_i32_e32 vcc, v14, v192
	v_add_u32_e32 v14, 10, v0
	s_nop 0
	v_cndmask_b32_e32 v101, v185, v101, vcc
	v_cmp_le_i32_e32 vcc, v14, v192
	v_add_u32_e32 v14, 42, v0
	s_nop 0
	v_cndmask_b32_e32 v86, v185, v86, vcc
	v_cmp_le_i32_e32 vcc, v14, v192
	v_add_u32_e32 v14, 11, v0
	s_nop 0
	v_cndmask_b32_e32 v102, v185, v102, vcc
	v_cmp_le_i32_e32 vcc, v14, v192
	v_add_u32_e32 v14, 43, v0
	s_nop 0
	v_cndmask_b32_e32 v87, v185, v87, vcc
	v_cmp_le_i32_e32 vcc, v14, v192
	v_add_u32_e32 v14, 16, v0
	s_nop 0
	v_cndmask_b32_e32 v103, v185, v103, vcc
	v_cmp_le_i32_e32 vcc, v14, v192
	v_add_u32_e32 v14, 48, v0
	s_nop 0
	v_cndmask_b32_e32 v88, v185, v88, vcc
	v_cmp_le_i32_e32 vcc, v14, v192
	v_add_u32_e32 v14, 17, v0
	s_nop 0
	v_cndmask_b32_e32 v104, v185, v104, vcc
	v_cmp_le_i32_e32 vcc, v14, v192
	v_add_u32_e32 v14, 49, v0
	s_nop 0
	v_cndmask_b32_e32 v89, v185, v89, vcc
	v_cmp_le_i32_e32 vcc, v14, v192
	v_add_u32_e32 v14, 18, v0
	s_nop 0
	v_cndmask_b32_e32 v105, v185, v105, vcc
	v_cmp_le_i32_e32 vcc, v14, v192
	v_add_u32_e32 v14, 50, v0
	s_nop 0
	v_cndmask_b32_e32 v90, v185, v90, vcc
	v_cmp_le_i32_e32 vcc, v14, v192
	v_add_u32_e32 v14, 19, v0
	s_nop 0
	v_cndmask_b32_e32 v106, v185, v106, vcc
	v_cmp_le_i32_e32 vcc, v14, v192
	v_add_u32_e32 v14, 51, v0
	s_nop 0
	v_cndmask_b32_e32 v91, v185, v91, vcc
	v_cmp_le_i32_e32 vcc, v14, v192
	v_add_u32_e32 v14, 24, v0
	s_nop 0
	v_cndmask_b32_e32 v107, v185, v107, vcc
	v_cmp_le_i32_e32 vcc, v14, v192
	v_add_u32_e32 v14, 56, v0
	s_nop 0
	v_cndmask_b32_e32 v92, v185, v92, vcc
	v_cmp_le_i32_e32 vcc, v14, v192
	v_add_u32_e32 v14, 25, v0
	s_nop 0
	v_cndmask_b32_e32 v108, v185, v108, vcc
	v_cmp_le_i32_e32 vcc, v14, v192
	v_add_u32_e32 v14, 57, v0
	s_nop 0
	v_cndmask_b32_e32 v93, v185, v93, vcc
	v_cmp_le_i32_e32 vcc, v14, v192
	v_add_u32_e32 v14, 26, v0
	s_nop 0
	v_cndmask_b32_e32 v109, v185, v109, vcc
	v_cmp_le_i32_e32 vcc, v14, v192
	v_add_u32_e32 v14, 58, v0
	s_nop 0
	v_cndmask_b32_e32 v94, v185, v94, vcc
	v_cmp_le_i32_e32 vcc, v14, v192
	v_add_u32_e32 v14, 27, v0
	v_add_u32_e32 v0, 59, v0
	v_cndmask_b32_e32 v110, v185, v110, vcc
	v_cmp_le_i32_e32 vcc, v14, v192
	s_nop 1
	v_cndmask_b32_e32 v95, v185, v95, vcc
	v_cmp_le_i32_e32 vcc, v0, v192
	s_nop 1
	v_cndmask_b32_e32 v111, v185, v111, vcc

.LBB0_1084:
	s_waitcnt lgkmcnt(0)
	s_barrier
	s_setprio 1
	v_add_u32_e32 v14, s50, v188
	s_waitcnt vmcnt(3)
	ds_write_b128 v14, v[136:139]
	v_add_u32_e32 v14, s50, v186
	v_add_u32_e32 v15, v14, v175
	v_add_u32_e32 v14, v14, v187
	ds_write_b128 v15, v[128:131] offset:9216
	ds_write_b128 v14, v[132:135] offset:9216
	s_and_b64 vcc, exec, s[4:5]
	s_cbranch_vccnz .LBB0_1086
	v_add_u32_e32 v249, s55, v190
	v_mfma_f32_32x32x16_bf16 v[64:79], v[196:199], v[156:159], v[64:79]
	ds_read_b128 v[196:199], v248 offset:9280
	v_mfma_f32_32x32x16_bf16 v[48:63], v[200:203], v[156:159], v[48:63]
	ds_read_b128 v[200:203], v248 offset:13888
	v_mfma_f32_32x32x16_bf16 v[32:47], v[204:207], v[156:159], v[32:47]
	ds_read_b128 v[204:207], v248 offset:18496
	v_mfma_f32_32x32x16_bf16 v[16:31], v[208:211], v[156:159], v[16:31]
	ds_read_b128 v[208:211], v248 offset:23104
	v_mfma_f32_32x32x16_bf16 v[64:79], v[212:215], v[160:163], v[64:79]
	ds_read_b128 v[212:215], v248 offset:9312
	v_mfma_f32_32x32x16_bf16 v[48:63], v[216:219], v[160:163], v[48:63]
	ds_read_b128 v[216:219], v248 offset:13920
	v_mfma_f32_32x32x16_bf16 v[32:47], v[220:223], v[160:163], v[32:47]
	ds_read_b128 v[220:223], v248 offset:18528
	v_mfma_f32_32x32x16_bf16 v[16:31], v[224:227], v[160:163], v[16:31]
	ds_read_b128 v[224:227], v248 offset:23136
	s_waitcnt lgkmcnt(7)
	v_mfma_f32_32x32x16_bf16 v[64:79], v[196:199], v[164:167], v[64:79]
	ds_read_b128 v[196:199], v249
	s_waitcnt lgkmcnt(7)
	v_mfma_f32_32x32x16_bf16 v[48:63], v[200:203], v[164:167], v[48:63]
	ds_read_b128 v[200:203], v249 offset:4608
	s_waitcnt lgkmcnt(7)
	v_mfma_f32_32x32x16_bf16 v[32:47], v[204:207], v[164:167], v[32:47]
	ds_read_b128 v[204:207], v249 offset:32
	s_waitcnt lgkmcnt(7)
	v_mfma_f32_32x32x16_bf16 v[16:31], v[208:211], v[164:167], v[16:31]
	ds_read_b128 v[208:211], v249 offset:4640
	s_waitcnt lgkmcnt(7)
	v_mfma_f32_32x32x16_bf16 v[64:79], v[212:215], v[168:171], v[64:79]
	ds_read_b128 v[212:215], v249 offset:64
	s_waitcnt lgkmcnt(7)
	v_mfma_f32_32x32x16_bf16 v[48:63], v[216:219], v[168:171], v[48:63]
	ds_read_b128 v[216:219], v249 offset:4672
	s_waitcnt lgkmcnt(7)
	v_mfma_f32_32x32x16_bf16 v[32:47], v[220:223], v[168:171], v[32:47]
	ds_read_b128 v[220:223], v249 offset:96
	s_waitcnt lgkmcnt(7)
	v_mfma_f32_32x32x16_bf16 v[16:31], v[224:227], v[168:171], v[16:31]
	ds_read_b128 v[224:227], v249 offset:4704
.LBB0_1086:
	s_add_i32 s0, s54, 1
	s_cmp_lt_u32 s0, s44
	s_cselect_b64 s[0:1], -1, 0
	s_add_i32 s4, s56, 33
	s_cmp_le_i32 s4, s35
	s_cselect_b64 s[4:5], -1, 0
	s_or_b64 s[4:5], s[16:17], s[4:5]
	s_and_b64 s[0:1], s[0:1], s[4:5]
	s_andn2_b64 vcc, exec, s[0:1]
	v_add_u32_e32 v0, s55, v190
	s_cbranch_vccnz .LBB0_1088
	s_waitcnt lgkmcnt(7)
	v_mfma_f32_32x32x16_bf16 v[80:95], v[196:199], v[232:235], v[112:127]
	s_waitcnt lgkmcnt(6)
	v_mfma_f32_32x32x16_bf16 v[96:111], v[200:203], v[232:235], v[112:127]
	s_waitcnt lgkmcnt(5)
	v_mfma_f32_32x32x16_bf16 v[80:95], v[204:207], v[236:239], v[80:95]
	s_waitcnt lgkmcnt(4)
	v_mfma_f32_32x32x16_bf16 v[96:111], v[208:211], v[236:239], v[96:111]
	s_waitcnt lgkmcnt(3)
	v_mfma_f32_32x32x16_bf16 v[80:95], v[212:215], v[240:243], v[80:95]
	s_waitcnt lgkmcnt(2)
	v_mfma_f32_32x32x16_bf16 v[96:111], v[216:219], v[240:243], v[96:111]
	s_waitcnt lgkmcnt(1)
	v_mfma_f32_32x32x16_bf16 v[80:95], v[220:223], v[244:247], v[80:95]
	s_waitcnt lgkmcnt(0)
	v_mfma_f32_32x32x16_bf16 v[96:111], v[224:227], v[244:247], v[96:111]
.LBB0_1088:
	s_setprio 0
	s_add_i32 s0, s54, 4
	s_cmp_lt_u32 s54, s43
	s_cselect_b32 s0, s0, s45
	s_lshl_b32 s8, s0, 6
	v_add_u32_e32 v14, s8, v174
	v_ashrrev_i32_e32 v15, 31, v14
	v_lshlrev_b64 v[14:15], 10, v[14:15]
	v_lshl_add_u64 v[132:133], s[8:9], 1, v[176:177]
	s_waitcnt lgkmcnt(0)
	s_barrier
	v_lshl_add_u64 v[14:15], v[182:183], 0, v[14:15]
	v_lshl_add_u64 v[128:129], v[132:133], 0, v[178:179]
	global_load_dwordx4 v[136:139], v[14:15], off
	s_nop 0
	global_load_dwordx4 v[128:131], v[128:129], off
	v_lshl_add_u64 v[14:15], v[132:133], 0, v[180:181]
	global_load_dwordx4 v[132:135], v[14:15], off
	v_add_u32_e32 v248, s55, v190
	ds_read_b128 v[196:199], v248 offset:9216
	ds_read_b128 v[200:203], v248 offset:13824
	ds_read_b128 v[204:207], v248 offset:18432
	ds_read_b128 v[208:211], v248 offset:23040
	ds_read_b128 v[212:215], v248 offset:9248
	ds_read_b128 v[216:219], v248 offset:13856
	ds_read_b128 v[220:223], v248 offset:18464
	ds_read_b128 v[224:227], v248 offset:23072
	s_add_i32 s57, s57, 1
	s_cmp_lt_i32 s57, 0
	s_cselect_b64 s[0:1], -1, 0
	s_add_i32 s4, s56, 64
	s_cmp_le_i32 s4, s46
	s_cselect_b64 s[4:5], -1, 0
	s_or_b64 s[0:1], s[0:1], s[4:5]
	v_cndmask_b32_e64 v14, 0, 1, s[0:1]
	v_cmp_ne_u32_e64 s[4:5], 1, v14
	s_andn2_b64 vcc, exec, s[0:1]
	s_cbranch_vccnz .LBB0_1094
	s_cmp_lt_i32 s57, 0
	s_cbranch_scc1 .LBB0_1091
	v_add_u32_e32 v14, s47, v194
	v_add_u32_e32 v140, 0x60, v14
	v_add_u32_e32 v15, 64, v14
	v_cmp_le_i32_e32 vcc, v140, v192
	s_nop 1
	v_cndmask_b32_e32 v96, v185, v96, vcc
	v_cmp_lt_i32_e32 vcc, v15, v192
	s_nop 1
	v_cndmask_b32_e32 v81, v185, v81, vcc
	v_cmp_le_i32_e32 vcc, v15, v192
	v_add_u32_e32 v15, 0x61, v14
	s_nop 0
	v_cndmask_b32_e32 v80, v185, v80, vcc
	v_cmp_le_i32_e32 vcc, v15, v192
	v_add_u32_e32 v15, 0x42, v14
	s_nop 0
	v_cndmask_b32_e32 v97, v185, v97, vcc
	v_cmp_le_i32_e32 vcc, v15, v192
	v_add_u32_e32 v15, 0x62, v14
	s_nop 0
	v_cndmask_b32_e32 v82, v185, v82, vcc
	v_cmp_le_i32_e32 vcc, v15, v192
	v_add_u32_e32 v15, 0x43, v14
	s_nop 0
	v_cndmask_b32_e32 v98, v185, v98, vcc
	v_cmp_le_i32_e32 vcc, v15, v192
	v_add_u32_e32 v15, 0x63, v14
	s_nop 0
	v_cndmask_b32_e32 v83, v185, v83, vcc
	v_cmp_le_i32_e32 vcc, v15, v192
	v_add_u32_e32 v15, 0x48, v14
	s_nop 0
	v_cndmask_b32_e32 v99, v185, v99, vcc
	v_cmp_le_i32_e32 vcc, v15, v192
	v_add_u32_e32 v15, 0x68, v14
	s_nop 0
	v_cndmask_b32_e32 v84, v185, v84, vcc
	v_cmp_le_i32_e32 vcc, v15, v192
	v_add_u32_e32 v15, 0x49, v14
	s_nop 0
	v_cndmask_b32_e32 v100, v185, v100, vcc
	v_cmp_le_i32_e32 vcc, v15, v192
	v_add_u32_e32 v15, 0x69, v14
	s_nop 0
	v_cndmask_b32_e32 v85, v185, v85, vcc
	v_cmp_le_i32_e32 vcc, v15, v192
	v_add_u32_e32 v15, 0x4a, v14
	s_nop 0
	v_cndmask_b32_e32 v101, v185, v101, vcc
	v_cmp_le_i32_e32 vcc, v15, v192
	v_add_u32_e32 v15, 0x6a, v14
	s_nop 0
	v_cndmask_b32_e32 v86, v185, v86, vcc
	v_cmp_le_i32_e32 vcc, v15, v192
	v_add_u32_e32 v15, 0x4b, v14
	s_nop 0
	v_cndmask_b32_e32 v102, v185, v102, vcc
	v_cmp_le_i32_e32 vcc, v15, v192
	v_add_u32_e32 v15, 0x6b, v14
	s_nop 0
	v_cndmask_b32_e32 v87, v185, v87, vcc
	v_cmp_le_i32_e32 vcc, v15, v192
	v_add_u32_e32 v15, 0x50, v14
	s_nop 0
	v_cndmask_b32_e32 v103, v185, v103, vcc
	v_cmp_le_i32_e32 vcc, v15, v192
	v_add_u32_e32 v15, 0x70, v14
	s_nop 0
	v_cndmask_b32_e32 v88, v185, v88, vcc
	v_cmp_le_i32_e32 vcc, v15, v192
	v_add_u32_e32 v15, 0x51, v14
	s_nop 0
	v_cndmask_b32_e32 v104, v185, v104, vcc
	v_cmp_le_i32_e32 vcc, v15, v192
	v_add_u32_e32 v15, 0x71, v14
	s_nop 0
	v_cndmask_b32_e32 v89, v185, v89, vcc
	v_cmp_le_i32_e32 vcc, v15, v192
	v_add_u32_e32 v15, 0x52, v14
	s_nop 0
	v_cndmask_b32_e32 v105, v185, v105, vcc
	v_cmp_le_i32_e32 vcc, v15, v192
	v_add_u32_e32 v15, 0x72, v14
	s_nop 0
	v_cndmask_b32_e32 v90, v185, v90, vcc
	v_cmp_le_i32_e32 vcc, v15, v192
	v_add_u32_e32 v15, 0x53, v14
	s_nop 0
	v_cndmask_b32_e32 v106, v185, v106, vcc
	v_cmp_le_i32_e32 vcc, v15, v192
	v_add_u32_e32 v15, 0x73, v14
	s_nop 0
	v_cndmask_b32_e32 v91, v185, v91, vcc
	v_cmp_le_i32_e32 vcc, v15, v192
	v_add_u32_e32 v15, 0x58, v14
	s_nop 0
	v_cndmask_b32_e32 v107, v185, v107, vcc
	v_cmp_le_i32_e32 vcc, v15, v192
	v_add_u32_e32 v15, 0x78, v14
	s_nop 0
	v_cndmask_b32_e32 v92, v185, v92, vcc
	v_cmp_le_i32_e32 vcc, v15, v192
	v_add_u32_e32 v15, 0x59, v14
	s_nop 0
	v_cndmask_b32_e32 v108, v185, v108, vcc
	v_cmp_le_i32_e32 vcc, v15, v192
	v_add_u32_e32 v15, 0x79, v14
	s_nop 0
	v_cndmask_b32_e32 v93, v185, v93, vcc
	v_cmp_le_i32_e32 vcc, v15, v192
	v_add_u32_e32 v15, 0x5a, v14
	s_nop 0
	v_cndmask_b32_e32 v109, v185, v109, vcc
	v_cmp_le_i32_e32 vcc, v15, v192
	v_add_u32_e32 v15, 0x7a, v14
	s_nop 0
	v_cndmask_b32_e32 v94, v185, v94, vcc
	v_cmp_le_i32_e32 vcc, v15, v192
	v_add_u32_e32 v15, 0x5b, v14
	v_add_u32_e32 v14, 0x7b, v14
	v_cndmask_b32_e32 v110, v185, v110, vcc
	v_cmp_le_i32_e32 vcc, v15, v192
	s_nop 1
	v_cndmask_b32_e32 v95, v185, v95, vcc
	v_cmp_le_i32_e32 vcc, v14, v192
	s_nop 1
	v_cndmask_b32_e32 v111, v185, v111, vcc

.LBB0_1094:
	s_waitcnt lgkmcnt(0)
	s_barrier
	s_setprio 1
	v_add_u32_e32 v0, s51, v188
	s_waitcnt vmcnt(5)
	ds_write_b128 v0, v[10:13]
	v_add_u32_e32 v0, s51, v186
	v_add_u32_e32 v10, v0, v175
	v_add_u32_e32 v0, v0, v187
	s_waitcnt vmcnt(4)
	ds_write_b128 v10, v[2:5] offset:9216
	s_waitcnt vmcnt(3)
	ds_write_b128 v0, v[6:9] offset:9216
	s_and_b64 vcc, exec, s[4:5]
	s_cbranch_vccnz .LBB0_1096
	v_add_u32_e32 v249, s50, v190
	v_mfma_f32_32x32x16_bf16 v[64:79], v[196:199], v[140:143], v[64:79]
	ds_read_b128 v[196:199], v248 offset:9280
	v_mfma_f32_32x32x16_bf16 v[48:63], v[200:203], v[140:143], v[48:63]
	ds_read_b128 v[200:203], v248 offset:13888
	v_mfma_f32_32x32x16_bf16 v[32:47], v[204:207], v[140:143], v[32:47]
	ds_read_b128 v[204:207], v248 offset:18496
	v_mfma_f32_32x32x16_bf16 v[16:31], v[208:211], v[140:143], v[16:31]
	ds_read_b128 v[208:211], v248 offset:23104
	v_mfma_f32_32x32x16_bf16 v[64:79], v[212:215], v[144:147], v[64:79]
	ds_read_b128 v[212:215], v248 offset:9312
	v_mfma_f32_32x32x16_bf16 v[48:63], v[216:219], v[144:147], v[48:63]
	ds_read_b128 v[216:219], v248 offset:13920
	v_mfma_f32_32x32x16_bf16 v[32:47], v[220:223], v[144:147], v[32:47]
	ds_read_b128 v[220:223], v248 offset:18528
	v_mfma_f32_32x32x16_bf16 v[16:31], v[224:227], v[144:147], v[16:31]
	ds_read_b128 v[224:227], v248 offset:23136
	s_waitcnt lgkmcnt(7)
	v_mfma_f32_32x32x16_bf16 v[64:79], v[196:199], v[148:151], v[64:79]
	ds_read_b128 v[196:199], v249
	s_waitcnt lgkmcnt(7)
	v_mfma_f32_32x32x16_bf16 v[48:63], v[200:203], v[148:151], v[48:63]
	ds_read_b128 v[200:203], v249 offset:4608
	s_waitcnt lgkmcnt(7)
	v_mfma_f32_32x32x16_bf16 v[32:47], v[204:207], v[148:151], v[32:47]
	ds_read_b128 v[204:207], v249 offset:32
	s_waitcnt lgkmcnt(7)
	v_mfma_f32_32x32x16_bf16 v[16:31], v[208:211], v[148:151], v[16:31]
	ds_read_b128 v[208:211], v249 offset:4640
	s_waitcnt lgkmcnt(7)
	v_mfma_f32_32x32x16_bf16 v[64:79], v[212:215], v[152:155], v[64:79]
	ds_read_b128 v[212:215], v249 offset:64
	s_waitcnt lgkmcnt(7)
	v_mfma_f32_32x32x16_bf16 v[48:63], v[216:219], v[152:155], v[48:63]
	ds_read_b128 v[216:219], v249 offset:4672
	s_waitcnt lgkmcnt(7)
	v_mfma_f32_32x32x16_bf16 v[32:47], v[220:223], v[152:155], v[32:47]
	ds_read_b128 v[220:223], v249 offset:96
	s_waitcnt lgkmcnt(7)
	v_mfma_f32_32x32x16_bf16 v[16:31], v[224:227], v[152:155], v[16:31]
	ds_read_b128 v[224:227], v249 offset:4704
.LBB0_1096:
	s_add_i32 s54, s54, 2
	s_cmp_ge_u32 s54, s44
	s_cselect_b64 s[4:5], -1, 0
	s_cmp_lt_u32 s54, s44
	s_cselect_b64 s[0:1], -1, 0
	s_cmp_lt_i32 s57, -1
	s_cselect_b64 s[16:17], -1, 0
	s_addk_i32 s56, 0x61
	s_cmp_le_i32 s56, s35
	s_cselect_b64 s[18:19], -1, 0
	s_or_b64 s[16:17], s[16:17], s[18:19]
	s_and_b64 s[0:1], s[0:1], s[16:17]
	s_andn2_b64 vcc, exec, s[0:1]
	s_cbranch_vccnz .LBB0_1098
	s_waitcnt lgkmcnt(7)
	v_mfma_f32_32x32x16_bf16 v[80:95], v[196:199], v[232:235], v[112:127]
	s_waitcnt lgkmcnt(6)
	v_mfma_f32_32x32x16_bf16 v[96:111], v[200:203], v[232:235], v[112:127]
	s_waitcnt lgkmcnt(5)
	v_mfma_f32_32x32x16_bf16 v[80:95], v[204:207], v[236:239], v[80:95]
	s_waitcnt lgkmcnt(4)
	v_mfma_f32_32x32x16_bf16 v[96:111], v[208:211], v[236:239], v[96:111]
	s_waitcnt lgkmcnt(3)
	v_mfma_f32_32x32x16_bf16 v[80:95], v[212:215], v[240:243], v[80:95]
	s_waitcnt lgkmcnt(2)
	v_mfma_f32_32x32x16_bf16 v[96:111], v[216:219], v[240:243], v[96:111]
	s_waitcnt lgkmcnt(1)
	v_mfma_f32_32x32x16_bf16 v[80:95], v[220:223], v[244:247], v[80:95]
	s_waitcnt lgkmcnt(0)
	v_mfma_f32_32x32x16_bf16 v[96:111], v[224:227], v[244:247], v[96:111]
.LBB0_1098:
	s_setprio 0
	s_waitcnt lgkmcnt(0)
	s_barrier
	s_addk_i32 s47, 0x80
	s_and_b64 vcc, exec, s[4:5]
	s_cbranch_vccnz .LBB0_1100
	s_mov_b32 s0, s50
	s_mov_b32 s50, s55
	s_branch .LBB0_1072
